# scan 2-step inner loop head aligned to 64 bytes (placement), otherwise identical to v49
# baseline (speedup 1.0000x reference)
.LBB0_227:
	s_add_i32 s41, s40, -2
	s_add_i32 s44, s12, 2
	s_and_b64 s[42:43], s[4:5], exec
	s_cselect_b32 s41, s41, s44
	s_lshl_b32 s80, s41, 17
	v_lshl_add_u64 v[148:149], v[146:147], 0, s[80:81]
	v_lshl_add_u64 v[170:171], v[148:149], 0, v[136:137]
	v_lshl_add_u64 v[148:149], v[148:149], 0, v[138:139]
	v_cvt_pk_bf16_f32 v196, v108, v109
	v_cvt_pk_bf16_f32 v197, v110, v111
	v_cvt_pk_bf16_f32 v198, v100, v101
	v_cvt_pk_bf16_f32 v199, v102, v103
	v_cvt_pk_bf16_f32 v200, v104, v105
	v_cvt_pk_bf16_f32 v201, v106, v107
	v_cvt_pk_bf16_f32 v202, v96, v97
	v_cvt_pk_bf16_f32 v203, v98, v99
	s_nop 1
	v_permlane16_swap_b32_e32 v196, v198
	v_permlane16_swap_b32_e32 v197, v199
	v_permlane16_swap_b32_e32 v200, v202
	v_permlane16_swap_b32_e32 v201, v203
	global_store_dwordx4 v[170:171], v[196:199], off
	global_store_dwordx4 v[148:149], v[200:203], off
	s_nop 1
	v_cvt_pk_bf16_f32 v196, v92, v93
	v_cvt_pk_bf16_f32 v197, v94, v95
	v_cvt_pk_bf16_f32 v198, v88, v89
	v_cvt_pk_bf16_f32 v199, v90, v91
	v_cvt_pk_bf16_f32 v200, v80, v81
	v_cvt_pk_bf16_f32 v201, v82, v83
	v_cvt_pk_bf16_f32 v202, v84, v85
	v_cvt_pk_bf16_f32 v203, v86, v87
	s_nop 1
	v_permlane16_swap_b32_e32 v196, v198
	v_permlane16_swap_b32_e32 v197, v199
	v_permlane16_swap_b32_e32 v200, v202
	v_permlane16_swap_b32_e32 v201, v203
	global_store_dwordx4 v[170:171], v[196:199], off offset:64
	global_store_dwordx4 v[148:149], v[200:203], off offset:64
	ds_read_b64_tr_b16 v[172:173], v165 offset:2560
	ds_read_b64_tr_b16 v[170:171], v165
	ds_read_b64_tr_b16 v[176:177], v166 offset:29184
	ds_read_b64_tr_b16 v[174:175], v166 offset:20480
	ds_read_b64_tr_b16 v[178:179], v165 offset:32
	ds_read_b64_tr_b16 v[180:181], v165 offset:2592
	ds_read_b64_tr_b16 v[182:183], v166 offset:20512
	ds_read_b64_tr_b16 v[184:185], v166 offset:29216
	v_pk_mul_f32 v[110:111], v[142:143], v[110:111]
	v_pk_mul_f32 v[108:109], v[144:145], v[108:109]
	v_pk_mul_f32 v[106:107], v[142:143], v[106:107]
	v_pk_mul_f32 v[104:105], v[144:145], v[104:105]
	v_pk_mul_f32 v[102:103], v[142:143], v[102:103]
	v_pk_mul_f32 v[100:101], v[144:145], v[100:101]
	v_pk_mul_f32 v[98:99], v[142:143], v[98:99]
	v_pk_mul_f32 v[96:97], v[144:145], v[96:97]
	s_waitcnt lgkmcnt(4)
	v_mfma_f32_16x16x32_bf16 v[108:111], v[170:173], v[174:177], v[108:111]
	v_mul_f32_e64 v94, v142, v94
	v_mul_f32_e64 v95, v143, v95
	v_pk_mul_f32 v[92:93], v[144:145], v[92:93]
	v_pk_mul_f32 v[82:83], v[142:143], v[82:83]
	s_waitcnt lgkmcnt(0)
	v_mfma_f32_16x16x32_bf16 v[104:107], v[170:173], v[182:185], v[104:107]
	ds_read_b64_tr_b16 v[170:171], v165 offset:64
	ds_read_b64_tr_b16 v[172:173], v165 offset:2624
	v_pk_mul_f32 v[80:81], v[144:145], v[80:81]
	v_mfma_f32_16x16x32_bf16 v[100:103], v[178:181], v[174:177], v[100:103]
	v_mul_f32_e64 v90, v142, v90
	v_mul_f32_e64 v91, v143, v91
	v_pk_mul_f32 v[88:89], v[144:145], v[88:89]
	v_pk_mul_f32 v[86:87], v[142:143], v[86:87]
	v_mfma_f32_16x16x32_bf16 v[96:99], v[178:181], v[182:185], v[96:99]
	ds_read_b64_tr_b16 v[180:181], v165 offset:2656
	ds_read_b64_tr_b16 v[178:179], v165 offset:96
	v_pk_mul_f32 v[84:85], v[144:145], v[84:85]
	s_waitcnt lgkmcnt(2)
	v_mfma_f32_16x16x32_bf16 v[92:95], v[170:173], v[174:177], v[92:95]
	s_add_i32 s40, s40, 2
	s_add_i32 s12, s12, -2
	s_cmp_gt_u32 s13, 29
	v_mfma_f32_16x16x32_bf16 v[80:83], v[170:173], v[182:185], v[80:83]
	ds_read_b64_tr_b16 v[170:171], v165 offset:5120
	ds_read_b64_tr_b16 v[172:173], v165 offset:7680
	s_waitcnt lgkmcnt(2)
	v_mfma_f32_16x16x32_bf16 v[88:91], v[178:181], v[174:177], v[88:91]
	v_mfma_f32_16x16x32_bf16 v[84:87], v[178:181], v[182:185], v[84:87]
	ds_read_b64_tr_b16 v[174:175], v166 offset:37888
	ds_read_b64_tr_b16 v[176:177], v166 offset:46592
	ds_read_b64_tr_b16 v[178:179], v166 offset:37920
	ds_read_b64_tr_b16 v[180:181], v166 offset:46624
	ds_read_b64_tr_b16 v[182:183], v165 offset:5152
	ds_read_b64_tr_b16 v[184:185], v165 offset:7712
	s_waitcnt lgkmcnt(4)
	v_mfma_f32_16x16x32_bf16 v[108:111], v[170:173], v[174:177], v[108:111]
	s_waitcnt lgkmcnt(2)
	v_mfma_f32_16x16x32_bf16 v[104:107], v[170:173], v[178:181], v[104:107]
	ds_read_b64_tr_b16 v[170:171], v165 offset:5184
	ds_read_b64_tr_b16 v[172:173], v165 offset:7744
	s_waitcnt lgkmcnt(2)
	v_mfma_f32_16x16x32_bf16 v[100:103], v[182:185], v[174:177], v[100:103]
	v_mfma_f32_16x16x32_bf16 v[96:99], v[182:185], v[178:181], v[96:99]
	ds_read_b64_tr_b16 v[184:185], v165 offset:7776
	ds_read_b64_tr_b16 v[182:183], v165 offset:5216
	s_waitcnt lgkmcnt(2)
	v_mfma_f32_16x16x32_bf16 v[92:95], v[170:173], v[174:177], v[92:95]
	v_mfma_f32_16x16x32_bf16 v[80:83], v[170:173], v[178:181], v[80:83]
	ds_read_b64_tr_b16 v[170:171], v165 offset:10240
	ds_read_b64_tr_b16 v[172:173], v165 offset:12800
	s_waitcnt lgkmcnt(2)
	v_mfma_f32_16x16x32_bf16 v[88:91], v[182:185], v[174:177], v[88:91]
	v_mfma_f32_16x16x32_bf16 v[84:87], v[182:185], v[178:181], v[84:87]
	ds_read_b64_tr_b16 v[174:175], v166 offset:55296
	ds_read_b64_tr_b16 v[176:177], v166 offset:64000
	ds_read_b64_tr_b16 v[178:179], v166 offset:55328
	ds_read_b64_tr_b16 v[180:181], v166 offset:64032
	ds_read_b64_tr_b16 v[182:183], v165 offset:10272
	ds_read_b64_tr_b16 v[184:185], v165 offset:12832
	s_waitcnt lgkmcnt(4)
	v_mfma_f32_16x16x32_bf16 v[108:111], v[170:173], v[174:177], v[108:111]
	s_waitcnt lgkmcnt(2)
	v_mfma_f32_16x16x32_bf16 v[104:107], v[170:173], v[178:181], v[104:107]
	ds_read_b64_tr_b16 v[170:171], v165 offset:10304
	ds_read_b64_tr_b16 v[172:173], v165 offset:12864
	s_waitcnt lgkmcnt(2)
	v_mfma_f32_16x16x32_bf16 v[100:103], v[182:185], v[174:177], v[100:103]
	v_mfma_f32_16x16x32_bf16 v[96:99], v[182:185], v[178:181], v[96:99]
	ds_read_b64_tr_b16 v[184:185], v165 offset:12896
	ds_read_b64_tr_b16 v[182:183], v165 offset:10336
	s_waitcnt lgkmcnt(2)
	v_mfma_f32_16x16x32_bf16 v[92:95], v[170:173], v[174:177], v[92:95]
	v_mfma_f32_16x16x32_bf16 v[80:83], v[170:173], v[178:181], v[80:83]
	ds_read_b64_tr_b16 v[170:171], v165 offset:15360
	ds_read_b64_tr_b16 v[172:173], v165 offset:17920
	s_waitcnt lgkmcnt(2)
	v_mfma_f32_16x16x32_bf16 v[88:91], v[182:185], v[174:177], v[88:91]
	v_mfma_f32_16x16x32_bf16 v[174:177], v[182:185], v[178:181], v[84:87]
	ds_read_b64_tr_b16 v[180:181], v167 offset:64000
	ds_read_b64_tr_b16 v[178:179], v167 offset:55296
	ds_read_b64_tr_b16 v[182:183], v167 offset:55328
	ds_read_b64_tr_b16 v[184:185], v167 offset:64032
	ds_read_b64_tr_b16 v[84:85], v165 offset:15392
	ds_read_b64_tr_b16 v[86:87], v165 offset:17952
	s_waitcnt lgkmcnt(4)
	v_mfma_f32_16x16x32_bf16 v[108:111], v[170:173], v[178:181], v[108:111]
	ds_read_b64_tr_b16 v[188:189], v165 offset:18016
	s_waitcnt lgkmcnt(3)
	v_mfma_f32_16x16x32_bf16 v[104:107], v[170:173], v[182:185], v[104:107]
	ds_read_b64_tr_b16 v[170:171], v165 offset:15424
	ds_read_b64_tr_b16 v[172:173], v165 offset:17984
	ds_read_b64_tr_b16 v[186:187], v165 offset:15456
	s_waitcnt lgkmcnt(4)
	v_mfma_f32_16x16x32_bf16 v[100:103], v[84:87], v[178:181], v[100:103]
	s_waitcnt lgkmcnt(0)
	s_barrier
	v_mfma_f32_16x16x32_bf16 v[96:99], v[84:87], v[182:185], v[96:99]
	v_mfma_f32_16x16x32_bf16 v[92:95], v[170:173], v[178:181], v[92:95]
	v_mfma_f32_16x16x32_bf16 v[84:87], v[170:173], v[182:185], v[80:83]
	v_mfma_f32_16x16x32_bf16 v[88:91], v[186:189], v[178:181], v[88:91]
	v_mfma_f32_16x16x32_bf16 v[80:83], v[186:189], v[182:185], v[174:177]
	s_cbranch_scc1 .LBB0_219
	.p2align 6
